# code placement: GEMM main-loop heads of k1/k6/k13 moved from 4 mod 8 to 0 mod 8 byte phase (one s_nop in front of the loop label)
# speedup vs baseline: 1.0088x; 1.0088x over previous
.LBB1_93:
	s_ashr_i32 s19, s18, 31
	s_lshl_b64 s[20:21], s[18:19], 19
	s_add_u32 s20, s33, s20
	s_addc_u32 s21, s34, s21
	s_and_b64 s[22:23], s[0:1], exec
	s_cselect_b32 s5, s21, s27
	s_cselect_b32 s19, s20, s26
	s_ashr_i32 s17, s16, 31
	s_lshl_b64 s[22:23], s[16:17], 19
	s_add_u32 s22, s35, s22
	s_addc_u32 s23, s36, s23
	s_and_b64 s[30:31], s[0:1], exec
	s_cselect_b32 s17, s23, s29
	s_cselect_b32 s25, s22, s28
	s_add_u32 s26, s26, 0x40080
	s_addc_u32 s27, s27, 0
	s_add_u32 s52, s28, 0x100
	s_addc_u32 s53, s29, 0
	s_mov_b32 s54, -2
	ds_read_b128 v[148:151], v153
	ds_read_b128 v[156:159], v153 offset:1024
	ds_read_b128 v[160:163], v153 offset:2048
	ds_read_b128 v[164:167], v153 offset:3072
	ds_read_b128 v[168:171], v154
	ds_read_b128 v[172:175], v154 offset:1024
	ds_read_b128 v[176:179], v154 offset:2048
	ds_read_b128 v[180:183], v154 offset:3072
	s_add_u32 s28, s26, 0xfffc0080
	s_addc_u32 s29, s27, -1
	s_cmp_eq_u32 s54, 12
	s_cselect_b32 s31, s5, s29
	s_cselect_b32 s30, s19, s28
	s_cselect_b32 s29, s17, s53
	s_cselect_b32 s28, s25, s52
	v_lshl_add_u64 v[216:217], s[26:27], 0, v[140:141]
	s_add_i32 m0, s38, 0xc000
	ds_read_b128 v[184:187], v155
	ds_read_b128 v[188:191], v155 offset:1024
	ds_read_b128 v[192:195], v155 offset:2048
	ds_read_b128 v[196:199], v155 offset:3072
	ds_read_b128 v[200:203], v155 offset:4096
	ds_read_b128 v[204:207], v155 offset:5120
	ds_read_b128 v[208:211], v155 offset:6144
	ds_read_b128 v[212:215], v155 offset:7168
	global_load_lds_dwordx4 v[216:217], off
	v_lshl_add_u64 v[216:217], s[26:27], 0, v[142:143]
	s_add_i32 m0, s38, 0xe000
	s_nop 0
	global_load_lds_dwordx4 v[216:217], off
	s_waitcnt vmcnt(8)
	s_waitcnt lgkmcnt(0)
	s_barrier
	s_waitcnt lgkmcnt(0)
	v_mfma_f32_16x16x32_bf16 v[124:127], v[148:151], v[184:187], 0
	v_mfma_f32_16x16x32_bf16 v[120:123], v[160:163], v[184:187], 0
	v_mfma_f32_16x16x32_bf16 v[108:111], v[148:151], v[192:195], 0
	v_mfma_f32_16x16x32_bf16 v[104:107], v[160:163], v[192:195], 0
	v_mfma_f32_16x16x32_bf16 v[92:95], v[148:151], v[200:203], 0
	v_mfma_f32_16x16x32_bf16 v[88:91], v[160:163], v[200:203], 0
	v_mfma_f32_16x16x32_bf16 v[76:79], v[148:151], v[208:211], 0
	v_mfma_f32_16x16x32_bf16 v[72:75], v[160:163], v[208:211], 0
	v_mfma_f32_16x16x32_bf16 v[124:127], v[156:159], v[188:191], v[124:127]
	v_mfma_f32_16x16x32_bf16 v[120:123], v[164:167], v[188:191], v[120:123]
	v_mfma_f32_16x16x32_bf16 v[108:111], v[156:159], v[196:199], v[108:111]
	v_mfma_f32_16x16x32_bf16 v[104:107], v[164:167], v[196:199], v[104:107]
	v_mfma_f32_16x16x32_bf16 v[92:95], v[156:159], v[204:207], v[92:95]
	v_mfma_f32_16x16x32_bf16 v[88:91], v[164:167], v[204:207], v[88:91]
	v_mfma_f32_16x16x32_bf16 v[76:79], v[156:159], v[212:215], v[76:79]
	v_mfma_f32_16x16x32_bf16 v[72:75], v[164:167], v[212:215], v[72:75]
	v_mfma_f32_16x16x32_bf16 v[116:119], v[168:171], v[184:187], 0
	v_mfma_f32_16x16x32_bf16 v[112:115], v[176:179], v[184:187], 0
	v_mfma_f32_16x16x32_bf16 v[100:103], v[168:171], v[192:195], 0
	v_mfma_f32_16x16x32_bf16 v[96:99], v[176:179], v[192:195], 0
	v_mfma_f32_16x16x32_bf16 v[84:87], v[168:171], v[200:203], 0
	v_mfma_f32_16x16x32_bf16 v[80:83], v[176:179], v[200:203], 0
	v_mfma_f32_16x16x32_bf16 v[68:71], v[168:171], v[208:211], 0
	v_mfma_f32_16x16x32_bf16 v[64:67], v[176:179], v[208:211], 0
	v_mfma_f32_16x16x32_bf16 v[116:119], v[172:175], v[188:191], v[116:119]
	v_mfma_f32_16x16x32_bf16 v[112:115], v[180:183], v[188:191], v[112:115]
	v_mfma_f32_16x16x32_bf16 v[100:103], v[172:175], v[196:199], v[100:103]
	v_mfma_f32_16x16x32_bf16 v[96:99], v[180:183], v[196:199], v[96:99]
	v_mfma_f32_16x16x32_bf16 v[84:87], v[172:175], v[204:207], v[84:87]
	v_mfma_f32_16x16x32_bf16 v[80:83], v[180:183], v[204:207], v[80:83]
	v_mfma_f32_16x16x32_bf16 v[68:71], v[172:175], v[212:215], v[68:71]
	v_mfma_f32_16x16x32_bf16 v[64:67], v[180:183], v[212:215], v[64:67]
	s_barrier
	s_add_i32 s55, s48, s37
	v_lshl_add_u64 v[216:217], s[28:29], 0, v[130:131]
	s_mov_b32 m0, s55
	ds_read_b128 v[184:187], v155 offset:16384
	ds_read_b128 v[188:191], v155 offset:17408
	ds_read_b128 v[192:195], v155 offset:18432
	ds_read_b128 v[196:199], v155 offset:19456
	ds_read_b128 v[200:203], v155 offset:20480
	ds_read_b128 v[204:207], v155 offset:21504
	ds_read_b128 v[208:211], v155 offset:22528
	ds_read_b128 v[212:215], v155 offset:23552
	global_load_lds_dwordx4 v[216:217], off
	s_add_i32 m0, s55, 0x2000
	s_add_u32 s56, s28, 0x40000
	v_lshl_add_u64 v[218:219], s[28:29], 0, v[134:135]
	s_addc_u32 s57, s29, 0
	s_add_i32 s55, s49, s37
	global_load_lds_dwordx4 v[218:219], off
	v_lshl_add_u64 v[220:221], s[56:57], 0, v[130:131]
	s_mov_b32 m0, s55
	v_lshl_add_u64 v[222:223], s[30:31], 0, v[132:133]
	global_load_lds_dwordx4 v[220:221], off
	v_lshl_add_u64 v[220:221], s[56:57], 0, v[134:135]
	s_add_i32 m0, s55, 0x2000
	s_nop 0
	global_load_lds_dwordx4 v[220:221], off
	v_lshl_add_u64 v[220:221], s[30:31], 0, v[128:129]
	s_mov_b32 m0, s38
	s_nop 0
	global_load_lds_dwordx4 v[220:221], off
	s_mov_b32 m0, s39
	s_nop 0
	global_load_lds_dwordx4 v[222:223], off
	s_waitcnt vmcnt(8)
	s_waitcnt lgkmcnt(0)
	s_barrier
	s_waitcnt lgkmcnt(0)
	v_mfma_f32_16x16x32_bf16 v[60:63], v[148:151], v[184:187], 0
	v_mfma_f32_16x16x32_bf16 v[56:59], v[160:163], v[184:187], 0
	v_mfma_f32_16x16x32_bf16 v[44:47], v[148:151], v[192:195], 0
	v_mfma_f32_16x16x32_bf16 v[40:43], v[160:163], v[192:195], 0
	v_mfma_f32_16x16x32_bf16 v[28:31], v[148:151], v[200:203], 0
	v_mfma_f32_16x16x32_bf16 v[24:27], v[160:163], v[200:203], 0
	v_mfma_f32_16x16x32_bf16 v[12:15], v[148:151], v[208:211], 0
	v_mfma_f32_16x16x32_bf16 v[8:11], v[160:163], v[208:211], 0
	v_mfma_f32_16x16x32_bf16 v[60:63], v[156:159], v[188:191], v[60:63]
	v_mfma_f32_16x16x32_bf16 v[56:59], v[164:167], v[188:191], v[56:59]
	v_mfma_f32_16x16x32_bf16 v[44:47], v[156:159], v[196:199], v[44:47]
	v_mfma_f32_16x16x32_bf16 v[40:43], v[164:167], v[196:199], v[40:43]
	v_mfma_f32_16x16x32_bf16 v[28:31], v[156:159], v[204:207], v[28:31]
	v_mfma_f32_16x16x32_bf16 v[24:27], v[164:167], v[204:207], v[24:27]
	v_mfma_f32_16x16x32_bf16 v[12:15], v[156:159], v[212:215], v[12:15]
	v_mfma_f32_16x16x32_bf16 v[8:11], v[164:167], v[212:215], v[8:11]
	v_mfma_f32_16x16x32_bf16 v[52:55], v[168:171], v[184:187], 0
	v_mfma_f32_16x16x32_bf16 v[48:51], v[176:179], v[184:187], 0
	v_mfma_f32_16x16x32_bf16 v[36:39], v[168:171], v[192:195], 0
	v_mfma_f32_16x16x32_bf16 v[32:35], v[176:179], v[192:195], 0
	v_mfma_f32_16x16x32_bf16 v[20:23], v[168:171], v[200:203], 0
	v_mfma_f32_16x16x32_bf16 v[16:19], v[176:179], v[200:203], 0
	v_mfma_f32_16x16x32_bf16 v[4:7], v[168:171], v[208:211], 0
	v_mfma_f32_16x16x32_bf16 v[0:3], v[176:179], v[208:211], 0
	v_mfma_f32_16x16x32_bf16 v[52:55], v[172:175], v[188:191], v[52:55]
	v_mfma_f32_16x16x32_bf16 v[48:51], v[180:183], v[188:191], v[48:51]
	v_mfma_f32_16x16x32_bf16 v[36:39], v[172:175], v[196:199], v[36:39]
	v_mfma_f32_16x16x32_bf16 v[32:35], v[180:183], v[196:199], v[32:35]
	v_mfma_f32_16x16x32_bf16 v[20:23], v[172:175], v[204:207], v[20:23]
	v_mfma_f32_16x16x32_bf16 v[16:19], v[180:183], v[204:207], v[16:19]
	v_mfma_f32_16x16x32_bf16 v[4:7], v[172:175], v[212:215], v[4:7]
	v_mfma_f32_16x16x32_bf16 v[0:3], v[180:183], v[212:215], v[0:3]
	s_barrier
	s_add_i32 s55, 0, 0x18000
	s_add_i32 s56, 0, 0x1c000
	v_add_u32_e32 v164, s55, v152
	v_add_u32_e32 v180, s56, v152
	ds_read_b128 v[148:151], v164
	ds_read_b128 v[156:159], v164 offset:1024
	ds_read_b128 v[160:163], v164 offset:2048
	ds_read_b128 v[164:167], v164 offset:3072
	ds_read_b128 v[168:171], v180
	ds_read_b128 v[172:175], v180 offset:1024
	ds_read_b128 v[176:179], v180 offset:2048
	ds_read_b128 v[180:183], v180 offset:3072
	s_add_u32 s30, s30, 0x40000
	s_addc_u32 s31, s31, 0
	s_mov_b32 m0, s40
	v_lshl_add_u64 v[224:225], s[30:31], 0, v[128:129]
	ds_read_b128 v[184:187], v155 offset:32768
	ds_read_b128 v[188:191], v155 offset:33792
	ds_read_b128 v[192:195], v155 offset:34816
	ds_read_b128 v[196:199], v155 offset:35840
	ds_read_b128 v[200:203], v155 offset:36864
	ds_read_b128 v[204:207], v155 offset:37888
	ds_read_b128 v[208:211], v155 offset:38912
	ds_read_b128 v[212:215], v155 offset:39936
	global_load_lds_dwordx4 v[224:225], off
	v_lshl_add_u64 v[224:225], s[30:31], 0, v[132:133]
	s_mov_b32 m0, s41
	s_nop 0
	global_load_lds_dwordx4 v[224:225], off
	s_waitcnt vmcnt(8)
	s_waitcnt lgkmcnt(0)
	s_barrier
	s_waitcnt lgkmcnt(0)
	v_mfma_f32_16x16x32_bf16 v[124:127], v[148:151], v[184:187], v[124:127]
	v_mfma_f32_16x16x32_bf16 v[120:123], v[160:163], v[184:187], v[120:123]
	v_mfma_f32_16x16x32_bf16 v[108:111], v[148:151], v[192:195], v[108:111]
	v_mfma_f32_16x16x32_bf16 v[104:107], v[160:163], v[192:195], v[104:107]
	v_mfma_f32_16x16x32_bf16 v[92:95], v[148:151], v[200:203], v[92:95]
	v_mfma_f32_16x16x32_bf16 v[88:91], v[160:163], v[200:203], v[88:91]
	v_mfma_f32_16x16x32_bf16 v[76:79], v[148:151], v[208:211], v[76:79]
	v_mfma_f32_16x16x32_bf16 v[72:75], v[160:163], v[208:211], v[72:75]
	v_mfma_f32_16x16x32_bf16 v[124:127], v[156:159], v[188:191], v[124:127]
	v_mfma_f32_16x16x32_bf16 v[120:123], v[164:167], v[188:191], v[120:123]
	v_mfma_f32_16x16x32_bf16 v[108:111], v[156:159], v[196:199], v[108:111]
	v_mfma_f32_16x16x32_bf16 v[104:107], v[164:167], v[196:199], v[104:107]
	v_mfma_f32_16x16x32_bf16 v[92:95], v[156:159], v[204:207], v[92:95]
	v_mfma_f32_16x16x32_bf16 v[88:91], v[164:167], v[204:207], v[88:91]
	v_mfma_f32_16x16x32_bf16 v[76:79], v[156:159], v[212:215], v[76:79]
	v_mfma_f32_16x16x32_bf16 v[72:75], v[164:167], v[212:215], v[72:75]
	v_mfma_f32_16x16x32_bf16 v[116:119], v[168:171], v[184:187], v[116:119]
	v_mfma_f32_16x16x32_bf16 v[112:115], v[176:179], v[184:187], v[112:115]
	v_mfma_f32_16x16x32_bf16 v[100:103], v[168:171], v[192:195], v[100:103]
	v_mfma_f32_16x16x32_bf16 v[96:99], v[176:179], v[192:195], v[96:99]
	v_mfma_f32_16x16x32_bf16 v[84:87], v[168:171], v[200:203], v[84:87]
	v_mfma_f32_16x16x32_bf16 v[80:83], v[176:179], v[200:203], v[80:83]
	v_mfma_f32_16x16x32_bf16 v[68:71], v[168:171], v[208:211], v[68:71]
	v_mfma_f32_16x16x32_bf16 v[64:67], v[176:179], v[208:211], v[64:67]
	v_mfma_f32_16x16x32_bf16 v[116:119], v[172:175], v[188:191], v[116:119]
	v_mfma_f32_16x16x32_bf16 v[112:115], v[180:183], v[188:191], v[112:115]
	v_mfma_f32_16x16x32_bf16 v[100:103], v[172:175], v[196:199], v[100:103]
	v_mfma_f32_16x16x32_bf16 v[96:99], v[180:183], v[196:199], v[96:99]
	v_mfma_f32_16x16x32_bf16 v[84:87], v[172:175], v[204:207], v[84:87]
	v_mfma_f32_16x16x32_bf16 v[80:83], v[180:183], v[204:207], v[80:83]
	v_mfma_f32_16x16x32_bf16 v[68:71], v[172:175], v[212:215], v[68:71]
	v_mfma_f32_16x16x32_bf16 v[64:67], v[180:183], v[212:215], v[64:67]
	s_barrier
	s_add_i32 s30, s55, s37
	v_lshl_add_u64 v[216:217], v[216:217], 0, s[12:13]
	s_mov_b32 m0, s30
	ds_read_b128 v[184:187], v155 offset:49152
	ds_read_b128 v[188:191], v155 offset:50176
	ds_read_b128 v[192:195], v155 offset:51200
	ds_read_b128 v[196:199], v155 offset:52224
	ds_read_b128 v[200:203], v155 offset:53248
	ds_read_b128 v[204:207], v155 offset:54272
	ds_read_b128 v[208:211], v155 offset:55296
	ds_read_b128 v[212:215], v155 offset:56320
	global_load_lds_dwordx4 v[216:217], off
	s_add_i32 m0, s30, 0x2000
	s_add_u32 s28, s28, 0x40080
	v_lshl_add_u64 v[216:217], v[218:219], 0, s[12:13]
	s_addc_u32 s29, s29, 0
	s_add_i32 s30, s56, s37
	global_load_lds_dwordx4 v[216:217], off
	v_lshl_add_u64 v[216:217], s[28:29], 0, v[130:131]
	s_mov_b32 m0, s30
	s_nop 0
	global_load_lds_dwordx4 v[216:217], off
	v_lshl_add_u64 v[216:217], s[28:29], 0, v[134:135]
	s_add_i32 m0, s30, 0x2000
	s_nop 0
	global_load_lds_dwordx4 v[216:217], off
	v_lshl_add_u64 v[216:217], v[220:221], 0, s[12:13]
	s_mov_b32 m0, s43
	s_nop 0
	global_load_lds_dwordx4 v[216:217], off
	v_lshl_add_u64 v[216:217], v[222:223], 0, s[12:13]
	s_mov_b32 m0, s44
	s_nop 0
	global_load_lds_dwordx4 v[216:217], off
	s_waitcnt vmcnt(8)
	s_waitcnt lgkmcnt(0)
	s_barrier
	s_waitcnt lgkmcnt(0)
	v_mfma_f32_16x16x32_bf16 v[60:63], v[148:151], v[184:187], v[60:63]
	v_mfma_f32_16x16x32_bf16 v[56:59], v[160:163], v[184:187], v[56:59]
	v_mfma_f32_16x16x32_bf16 v[44:47], v[148:151], v[192:195], v[44:47]
	v_mfma_f32_16x16x32_bf16 v[40:43], v[160:163], v[192:195], v[40:43]
	v_mfma_f32_16x16x32_bf16 v[28:31], v[148:151], v[200:203], v[28:31]
	v_mfma_f32_16x16x32_bf16 v[24:27], v[160:163], v[200:203], v[24:27]
	v_mfma_f32_16x16x32_bf16 v[12:15], v[148:151], v[208:211], v[12:15]
	v_mfma_f32_16x16x32_bf16 v[8:11], v[160:163], v[208:211], v[8:11]
	v_mfma_f32_16x16x32_bf16 v[60:63], v[156:159], v[188:191], v[60:63]
	v_mfma_f32_16x16x32_bf16 v[56:59], v[164:167], v[188:191], v[56:59]
	v_mfma_f32_16x16x32_bf16 v[44:47], v[156:159], v[196:199], v[44:47]
	v_mfma_f32_16x16x32_bf16 v[40:43], v[164:167], v[196:199], v[40:43]
	v_mfma_f32_16x16x32_bf16 v[28:31], v[156:159], v[204:207], v[28:31]
	v_mfma_f32_16x16x32_bf16 v[24:27], v[164:167], v[204:207], v[24:27]
	v_mfma_f32_16x16x32_bf16 v[12:15], v[156:159], v[212:215], v[12:15]
	v_mfma_f32_16x16x32_bf16 v[8:11], v[164:167], v[212:215], v[8:11]
	v_mfma_f32_16x16x32_bf16 v[52:55], v[168:171], v[184:187], v[52:55]
	v_mfma_f32_16x16x32_bf16 v[48:51], v[176:179], v[184:187], v[48:51]
	v_mfma_f32_16x16x32_bf16 v[36:39], v[168:171], v[192:195], v[36:39]
	v_mfma_f32_16x16x32_bf16 v[32:35], v[176:179], v[192:195], v[32:35]
	v_mfma_f32_16x16x32_bf16 v[20:23], v[168:171], v[200:203], v[20:23]
	v_mfma_f32_16x16x32_bf16 v[16:19], v[176:179], v[200:203], v[16:19]
	v_mfma_f32_16x16x32_bf16 v[4:7], v[168:171], v[208:211], v[4:7]
	v_mfma_f32_16x16x32_bf16 v[0:3], v[176:179], v[208:211], v[0:3]
	v_mfma_f32_16x16x32_bf16 v[52:55], v[172:175], v[188:191], v[52:55]
	v_mfma_f32_16x16x32_bf16 v[48:51], v[180:183], v[188:191], v[48:51]
	v_mfma_f32_16x16x32_bf16 v[36:39], v[172:175], v[196:199], v[36:39]
	v_mfma_f32_16x16x32_bf16 v[32:35], v[180:183], v[196:199], v[32:35]
	v_mfma_f32_16x16x32_bf16 v[20:23], v[172:175], v[204:207], v[20:23]
	v_mfma_f32_16x16x32_bf16 v[16:19], v[180:183], v[204:207], v[16:19]
	v_mfma_f32_16x16x32_bf16 v[4:7], v[172:175], v[212:215], v[4:7]
	v_mfma_f32_16x16x32_bf16 v[0:3], v[180:183], v[212:215], v[0:3]
	s_barrier
	s_add_i32 s54, s54, 2
	s_add_u32 s26, s26, 0x100
	s_addc_u32 s27, s27, 0
	s_add_u32 s52, s52, 0x100
	s_addc_u32 s53, s53, 0
	s_cmp_gt_u32 s54, 13
	s_nop 0

.LBB6_19:
	s_ashr_i32 s17, s16, 31
	s_lshl_b64 s[18:19], s[16:17], 21
	s_add_u32 s18, s33, s18
	v_cmp_lt_i64_e64 s[4:5], s[4:5], v[142:143]
	s_addc_u32 s19, s34, s19
	s_and_b64 s[20:21], s[4:5], exec
	s_cselect_b32 s17, s19, s25
	s_cselect_b32 s53, s18, s24
	s_ashr_i32 s15, s14, 31
	s_lshl_b64 s[20:21], s[14:15], 21
	s_add_u32 s20, s6, s20
	s_addc_u32 s21, s7, s21
	s_and_b64 s[28:29], s[4:5], exec
	s_cselect_b32 s15, s21, s27
	s_cselect_b32 s54, s20, s26
	s_add_u32 s24, s24, 0x100080
	s_addc_u32 s25, s25, 0
	s_add_u32 s55, s26, 0x100
	s_addc_u32 s56, s27, 0
	s_mov_b32 s57, -2
	ds_read_b128 v[152:155], v149
	ds_read_b128 v[156:159], v149 offset:1024
	ds_read_b128 v[160:163], v149 offset:2048
	ds_read_b128 v[164:167], v149 offset:3072
	ds_read_b128 v[168:171], v150
	ds_read_b128 v[172:175], v150 offset:1024
	ds_read_b128 v[176:179], v150 offset:2048
	ds_read_b128 v[180:183], v150 offset:3072
	s_add_u32 s26, s24, 0xfff00080
	s_addc_u32 s27, s25, -1
	s_cmp_eq_u32 s57, 60
	s_cselect_b32 s29, s17, s27
	s_cselect_b32 s28, s53, s26
	s_cselect_b32 s27, s15, s56
	s_cselect_b32 s26, s54, s55
	v_lshl_add_u64 v[146:147], s[24:25], 0, v[138:139]
	s_add_i32 m0, s23, 0xc000
	ds_read_b128 v[184:187], v151
	ds_read_b128 v[188:191], v151 offset:1024
	ds_read_b128 v[192:195], v151 offset:2048
	ds_read_b128 v[196:199], v151 offset:3072
	ds_read_b128 v[200:203], v151 offset:4096
	ds_read_b128 v[204:207], v151 offset:5120
	ds_read_b128 v[208:211], v151 offset:6144
	ds_read_b128 v[212:215], v151 offset:7168
	global_load_lds_dwordx4 v[146:147], off
	v_lshl_add_u64 v[146:147], s[24:25], 0, v[140:141]
	s_add_i32 m0, s23, 0xe000
	s_nop 0
	global_load_lds_dwordx4 v[146:147], off
	s_waitcnt vmcnt(8)
	s_waitcnt lgkmcnt(0)
	s_barrier
	s_waitcnt lgkmcnt(0)
	v_mfma_f32_16x16x32_bf16 v[124:127], v[152:155], v[184:187], 0
	v_mfma_f32_16x16x32_bf16 v[120:123], v[160:163], v[184:187], 0
	v_mfma_f32_16x16x32_bf16 v[116:119], v[152:155], v[192:195], 0
	v_mfma_f32_16x16x32_bf16 v[108:111], v[160:163], v[192:195], 0
	v_mfma_f32_16x16x32_bf16 v[100:103], v[152:155], v[200:203], 0
	v_mfma_f32_16x16x32_bf16 v[92:95], v[160:163], v[200:203], 0
	v_mfma_f32_16x16x32_bf16 v[84:87], v[152:155], v[208:211], 0
	v_mfma_f32_16x16x32_bf16 v[76:79], v[160:163], v[208:211], 0
	v_mfma_f32_16x16x32_bf16 v[124:127], v[156:159], v[188:191], v[124:127]
	v_mfma_f32_16x16x32_bf16 v[120:123], v[164:167], v[188:191], v[120:123]
	v_mfma_f32_16x16x32_bf16 v[116:119], v[156:159], v[196:199], v[116:119]
	v_mfma_f32_16x16x32_bf16 v[108:111], v[164:167], v[196:199], v[108:111]
	v_mfma_f32_16x16x32_bf16 v[100:103], v[156:159], v[204:207], v[100:103]
	v_mfma_f32_16x16x32_bf16 v[92:95], v[164:167], v[204:207], v[92:95]
	v_mfma_f32_16x16x32_bf16 v[84:87], v[156:159], v[212:215], v[84:87]
	v_mfma_f32_16x16x32_bf16 v[76:79], v[164:167], v[212:215], v[76:79]
	v_mfma_f32_16x16x32_bf16 v[112:115], v[168:171], v[184:187], 0
	v_mfma_f32_16x16x32_bf16 v[104:107], v[176:179], v[184:187], 0
	v_mfma_f32_16x16x32_bf16 v[96:99], v[168:171], v[192:195], 0
	v_mfma_f32_16x16x32_bf16 v[88:91], v[176:179], v[192:195], 0
	v_mfma_f32_16x16x32_bf16 v[80:83], v[168:171], v[200:203], 0
	v_mfma_f32_16x16x32_bf16 v[72:75], v[176:179], v[200:203], 0
	v_mfma_f32_16x16x32_bf16 v[68:71], v[168:171], v[208:211], 0
	v_mfma_f32_16x16x32_bf16 v[64:67], v[176:179], v[208:211], 0
	v_mfma_f32_16x16x32_bf16 v[112:115], v[172:175], v[188:191], v[112:115]
	v_mfma_f32_16x16x32_bf16 v[104:107], v[180:183], v[188:191], v[104:107]
	v_mfma_f32_16x16x32_bf16 v[96:99], v[172:175], v[196:199], v[96:99]
	v_mfma_f32_16x16x32_bf16 v[88:91], v[180:183], v[196:199], v[88:91]
	v_mfma_f32_16x16x32_bf16 v[80:83], v[172:175], v[204:207], v[80:83]
	v_mfma_f32_16x16x32_bf16 v[72:75], v[180:183], v[204:207], v[72:75]
	v_mfma_f32_16x16x32_bf16 v[68:71], v[172:175], v[212:215], v[68:71]
	v_mfma_f32_16x16x32_bf16 v[64:67], v[180:183], v[212:215], v[64:67]
	s_barrier
	s_add_i32 s58, s45, s31
	v_lshl_add_u64 v[146:147], s[26:27], 0, v[130:131]
	s_mov_b32 m0, s58
	ds_read_b128 v[184:187], v151 offset:16384
	ds_read_b128 v[188:191], v151 offset:17408
	ds_read_b128 v[192:195], v151 offset:18432
	ds_read_b128 v[196:199], v151 offset:19456
	ds_read_b128 v[200:203], v151 offset:20480
	ds_read_b128 v[204:207], v151 offset:21504
	ds_read_b128 v[208:211], v151 offset:22528
	ds_read_b128 v[212:215], v151 offset:23552
	global_load_lds_dwordx4 v[146:147], off
	s_add_i32 m0, s58, 0x2000
	s_add_u32 s58, s26, 0x100000
	v_lshl_add_u64 v[216:217], s[26:27], 0, v[134:135]
	s_addc_u32 s59, s27, 0
	s_add_i32 s60, s46, s31
	global_load_lds_dwordx4 v[216:217], off
	v_lshl_add_u64 v[218:219], s[58:59], 0, v[130:131]
	s_mov_b32 m0, s60
	v_lshl_add_u64 v[220:221], s[28:29], 0, v[132:133]
	global_load_lds_dwordx4 v[218:219], off
	v_lshl_add_u64 v[218:219], s[58:59], 0, v[134:135]
	s_add_i32 m0, s60, 0x2000
	s_nop 0
	global_load_lds_dwordx4 v[218:219], off
	v_lshl_add_u64 v[218:219], s[28:29], 0, v[128:129]
	s_mov_b32 m0, s23
	s_nop 0
	global_load_lds_dwordx4 v[218:219], off
	s_mov_b32 m0, s35
	s_nop 0
	global_load_lds_dwordx4 v[220:221], off
	s_waitcnt vmcnt(8)
	s_waitcnt lgkmcnt(0)
	s_barrier
	s_waitcnt lgkmcnt(0)
	v_mfma_f32_16x16x32_bf16 v[60:63], v[152:155], v[184:187], 0
	v_mfma_f32_16x16x32_bf16 v[56:59], v[160:163], v[184:187], 0
	v_mfma_f32_16x16x32_bf16 v[52:55], v[152:155], v[192:195], 0
	v_mfma_f32_16x16x32_bf16 v[44:47], v[160:163], v[192:195], 0
	v_mfma_f32_16x16x32_bf16 v[36:39], v[152:155], v[200:203], 0
	v_mfma_f32_16x16x32_bf16 v[28:31], v[160:163], v[200:203], 0
	v_mfma_f32_16x16x32_bf16 v[20:23], v[152:155], v[208:211], 0
	v_mfma_f32_16x16x32_bf16 v[12:15], v[160:163], v[208:211], 0
	v_mfma_f32_16x16x32_bf16 v[60:63], v[156:159], v[188:191], v[60:63]
	v_mfma_f32_16x16x32_bf16 v[56:59], v[164:167], v[188:191], v[56:59]
	v_mfma_f32_16x16x32_bf16 v[52:55], v[156:159], v[196:199], v[52:55]
	v_mfma_f32_16x16x32_bf16 v[44:47], v[164:167], v[196:199], v[44:47]
	v_mfma_f32_16x16x32_bf16 v[36:39], v[156:159], v[204:207], v[36:39]
	v_mfma_f32_16x16x32_bf16 v[28:31], v[164:167], v[204:207], v[28:31]
	v_mfma_f32_16x16x32_bf16 v[20:23], v[156:159], v[212:215], v[20:23]
	v_mfma_f32_16x16x32_bf16 v[12:15], v[164:167], v[212:215], v[12:15]
	v_mfma_f32_16x16x32_bf16 v[48:51], v[168:171], v[184:187], 0
	v_mfma_f32_16x16x32_bf16 v[40:43], v[176:179], v[184:187], 0
	v_mfma_f32_16x16x32_bf16 v[32:35], v[168:171], v[192:195], 0
	v_mfma_f32_16x16x32_bf16 v[24:27], v[176:179], v[192:195], 0
	v_mfma_f32_16x16x32_bf16 v[16:19], v[168:171], v[200:203], 0
	v_mfma_f32_16x16x32_bf16 v[8:11], v[176:179], v[200:203], 0
	v_mfma_f32_16x16x32_bf16 v[4:7], v[168:171], v[208:211], 0
	v_mfma_f32_16x16x32_bf16 v[0:3], v[176:179], v[208:211], 0
	v_mfma_f32_16x16x32_bf16 v[48:51], v[172:175], v[188:191], v[48:51]
	v_mfma_f32_16x16x32_bf16 v[40:43], v[180:183], v[188:191], v[40:43]
	v_mfma_f32_16x16x32_bf16 v[32:35], v[172:175], v[196:199], v[32:35]
	v_mfma_f32_16x16x32_bf16 v[24:27], v[180:183], v[196:199], v[24:27]
	v_mfma_f32_16x16x32_bf16 v[16:19], v[172:175], v[204:207], v[16:19]
	v_mfma_f32_16x16x32_bf16 v[8:11], v[180:183], v[204:207], v[8:11]
	v_mfma_f32_16x16x32_bf16 v[4:7], v[172:175], v[212:215], v[4:7]
	v_mfma_f32_16x16x32_bf16 v[0:3], v[180:183], v[212:215], v[0:3]
	s_barrier
	s_add_i32 s58, 0, 0x18000
	s_add_i32 s59, 0, 0x1c000
	v_add_u32_e32 v164, s58, v148
	v_add_u32_e32 v180, s59, v148
	ds_read_b128 v[152:155], v164
	ds_read_b128 v[156:159], v164 offset:1024
	ds_read_b128 v[160:163], v164 offset:2048
	ds_read_b128 v[164:167], v164 offset:3072
	ds_read_b128 v[168:171], v180
	ds_read_b128 v[172:175], v180 offset:1024
	ds_read_b128 v[176:179], v180 offset:2048
	ds_read_b128 v[180:183], v180 offset:3072
	s_add_u32 s28, s28, 0x100000
	s_addc_u32 s29, s29, 0
	s_mov_b32 m0, s36
	v_lshl_add_u64 v[222:223], s[28:29], 0, v[128:129]
	ds_read_b128 v[184:187], v151 offset:32768
	ds_read_b128 v[188:191], v151 offset:33792
	ds_read_b128 v[192:195], v151 offset:34816
	ds_read_b128 v[196:199], v151 offset:35840
	ds_read_b128 v[200:203], v151 offset:36864
	ds_read_b128 v[204:207], v151 offset:37888
	ds_read_b128 v[208:211], v151 offset:38912
	ds_read_b128 v[212:215], v151 offset:39936
	global_load_lds_dwordx4 v[222:223], off
	v_lshl_add_u64 v[222:223], s[28:29], 0, v[132:133]
	s_mov_b32 m0, s37
	s_nop 0
	global_load_lds_dwordx4 v[222:223], off
	s_waitcnt vmcnt(8)
	s_waitcnt lgkmcnt(0)
	s_barrier
	s_waitcnt lgkmcnt(0)
	v_mfma_f32_16x16x32_bf16 v[124:127], v[152:155], v[184:187], v[124:127]
	v_mfma_f32_16x16x32_bf16 v[120:123], v[160:163], v[184:187], v[120:123]
	v_mfma_f32_16x16x32_bf16 v[116:119], v[152:155], v[192:195], v[116:119]
	v_mfma_f32_16x16x32_bf16 v[108:111], v[160:163], v[192:195], v[108:111]
	v_mfma_f32_16x16x32_bf16 v[100:103], v[152:155], v[200:203], v[100:103]
	v_mfma_f32_16x16x32_bf16 v[92:95], v[160:163], v[200:203], v[92:95]
	v_mfma_f32_16x16x32_bf16 v[84:87], v[152:155], v[208:211], v[84:87]
	v_mfma_f32_16x16x32_bf16 v[76:79], v[160:163], v[208:211], v[76:79]
	v_mfma_f32_16x16x32_bf16 v[124:127], v[156:159], v[188:191], v[124:127]
	v_mfma_f32_16x16x32_bf16 v[120:123], v[164:167], v[188:191], v[120:123]
	v_mfma_f32_16x16x32_bf16 v[116:119], v[156:159], v[196:199], v[116:119]
	v_mfma_f32_16x16x32_bf16 v[108:111], v[164:167], v[196:199], v[108:111]
	v_mfma_f32_16x16x32_bf16 v[100:103], v[156:159], v[204:207], v[100:103]
	v_mfma_f32_16x16x32_bf16 v[92:95], v[164:167], v[204:207], v[92:95]
	v_mfma_f32_16x16x32_bf16 v[84:87], v[156:159], v[212:215], v[84:87]
	v_mfma_f32_16x16x32_bf16 v[76:79], v[164:167], v[212:215], v[76:79]
	v_mfma_f32_16x16x32_bf16 v[112:115], v[168:171], v[184:187], v[112:115]
	v_mfma_f32_16x16x32_bf16 v[104:107], v[176:179], v[184:187], v[104:107]
	v_mfma_f32_16x16x32_bf16 v[96:99], v[168:171], v[192:195], v[96:99]
	v_mfma_f32_16x16x32_bf16 v[88:91], v[176:179], v[192:195], v[88:91]
	v_mfma_f32_16x16x32_bf16 v[80:83], v[168:171], v[200:203], v[80:83]
	v_mfma_f32_16x16x32_bf16 v[72:75], v[176:179], v[200:203], v[72:75]
	v_mfma_f32_16x16x32_bf16 v[68:71], v[168:171], v[208:211], v[68:71]
	v_mfma_f32_16x16x32_bf16 v[64:67], v[176:179], v[208:211], v[64:67]
	v_mfma_f32_16x16x32_bf16 v[112:115], v[172:175], v[188:191], v[112:115]
	v_mfma_f32_16x16x32_bf16 v[104:107], v[180:183], v[188:191], v[104:107]
	v_mfma_f32_16x16x32_bf16 v[96:99], v[172:175], v[196:199], v[96:99]
	v_mfma_f32_16x16x32_bf16 v[88:91], v[180:183], v[196:199], v[88:91]
	v_mfma_f32_16x16x32_bf16 v[80:83], v[172:175], v[204:207], v[80:83]
	v_mfma_f32_16x16x32_bf16 v[72:75], v[180:183], v[204:207], v[72:75]
	v_mfma_f32_16x16x32_bf16 v[68:71], v[172:175], v[212:215], v[68:71]
	v_mfma_f32_16x16x32_bf16 v[64:67], v[180:183], v[212:215], v[64:67]
	s_barrier
	s_add_i32 s28, s58, s31
	v_lshl_add_u64 v[146:147], v[146:147], 0, s[12:13]
	s_mov_b32 m0, s28
	ds_read_b128 v[184:187], v151 offset:49152
	ds_read_b128 v[188:191], v151 offset:50176
	ds_read_b128 v[192:195], v151 offset:51200
	ds_read_b128 v[196:199], v151 offset:52224
	ds_read_b128 v[200:203], v151 offset:53248
	ds_read_b128 v[204:207], v151 offset:54272
	ds_read_b128 v[208:211], v151 offset:55296
	ds_read_b128 v[212:215], v151 offset:56320
	global_load_lds_dwordx4 v[146:147], off
	s_add_i32 m0, s28, 0x2000
	s_add_u32 s26, s26, 0x100080
	v_lshl_add_u64 v[146:147], v[216:217], 0, s[12:13]
	s_addc_u32 s27, s27, 0
	s_add_i32 s28, s59, s31
	global_load_lds_dwordx4 v[146:147], off
	v_lshl_add_u64 v[146:147], s[26:27], 0, v[130:131]
	s_mov_b32 m0, s28
	s_nop 0
	global_load_lds_dwordx4 v[146:147], off
	v_lshl_add_u64 v[146:147], s[26:27], 0, v[134:135]
	s_add_i32 m0, s28, 0x2000
	s_nop 0
	global_load_lds_dwordx4 v[146:147], off
	v_lshl_add_u64 v[146:147], v[218:219], 0, s[12:13]
	s_mov_b32 m0, s40
	s_nop 0
	global_load_lds_dwordx4 v[146:147], off
	v_lshl_add_u64 v[146:147], v[220:221], 0, s[12:13]
	s_mov_b32 m0, s41
	s_nop 0
	global_load_lds_dwordx4 v[146:147], off
	s_waitcnt vmcnt(8)
	s_waitcnt lgkmcnt(0)
	s_barrier
	s_waitcnt lgkmcnt(0)
	v_mfma_f32_16x16x32_bf16 v[60:63], v[152:155], v[184:187], v[60:63]
	v_mfma_f32_16x16x32_bf16 v[56:59], v[160:163], v[184:187], v[56:59]
	v_mfma_f32_16x16x32_bf16 v[52:55], v[152:155], v[192:195], v[52:55]
	v_mfma_f32_16x16x32_bf16 v[44:47], v[160:163], v[192:195], v[44:47]
	v_mfma_f32_16x16x32_bf16 v[36:39], v[152:155], v[200:203], v[36:39]
	v_mfma_f32_16x16x32_bf16 v[28:31], v[160:163], v[200:203], v[28:31]
	v_mfma_f32_16x16x32_bf16 v[20:23], v[152:155], v[208:211], v[20:23]
	v_mfma_f32_16x16x32_bf16 v[12:15], v[160:163], v[208:211], v[12:15]
	v_mfma_f32_16x16x32_bf16 v[60:63], v[156:159], v[188:191], v[60:63]
	v_mfma_f32_16x16x32_bf16 v[56:59], v[164:167], v[188:191], v[56:59]
	v_mfma_f32_16x16x32_bf16 v[52:55], v[156:159], v[196:199], v[52:55]
	v_mfma_f32_16x16x32_bf16 v[44:47], v[164:167], v[196:199], v[44:47]
	v_mfma_f32_16x16x32_bf16 v[36:39], v[156:159], v[204:207], v[36:39]
	v_mfma_f32_16x16x32_bf16 v[28:31], v[164:167], v[204:207], v[28:31]
	v_mfma_f32_16x16x32_bf16 v[20:23], v[156:159], v[212:215], v[20:23]
	v_mfma_f32_16x16x32_bf16 v[12:15], v[164:167], v[212:215], v[12:15]
	v_mfma_f32_16x16x32_bf16 v[48:51], v[168:171], v[184:187], v[48:51]
	v_mfma_f32_16x16x32_bf16 v[40:43], v[176:179], v[184:187], v[40:43]
	v_mfma_f32_16x16x32_bf16 v[32:35], v[168:171], v[192:195], v[32:35]
	v_mfma_f32_16x16x32_bf16 v[24:27], v[176:179], v[192:195], v[24:27]
	v_mfma_f32_16x16x32_bf16 v[16:19], v[168:171], v[200:203], v[16:19]
	v_mfma_f32_16x16x32_bf16 v[8:11], v[176:179], v[200:203], v[8:11]
	v_mfma_f32_16x16x32_bf16 v[4:7], v[168:171], v[208:211], v[4:7]
	v_mfma_f32_16x16x32_bf16 v[0:3], v[176:179], v[208:211], v[0:3]
	v_mfma_f32_16x16x32_bf16 v[48:51], v[172:175], v[188:191], v[48:51]
	v_mfma_f32_16x16x32_bf16 v[40:43], v[180:183], v[188:191], v[40:43]
	v_mfma_f32_16x16x32_bf16 v[32:35], v[172:175], v[196:199], v[32:35]
	v_mfma_f32_16x16x32_bf16 v[24:27], v[180:183], v[196:199], v[24:27]
	v_mfma_f32_16x16x32_bf16 v[16:19], v[172:175], v[204:207], v[16:19]
	v_mfma_f32_16x16x32_bf16 v[8:11], v[180:183], v[204:207], v[8:11]
	v_mfma_f32_16x16x32_bf16 v[4:7], v[172:175], v[212:215], v[4:7]
	v_mfma_f32_16x16x32_bf16 v[0:3], v[180:183], v[212:215], v[0:3]
	s_barrier
	s_add_i32 s57, s57, 2
	s_add_u32 s24, s24, 0x100
	s_addc_u32 s25, s25, 0
	s_add_u32 s55, s55, 0x100
	s_addc_u32 s56, s56, 0
	s_cmp_gt_u32 s57, 61
	s_nop 0

.LBB13_19:
	s_ashr_i32 s17, s16, 31
	v_cmp_lt_i64_e32 vcc, s[0:1], v[142:143]
	s_lshl_b64 s[0:1], s[16:17], 21
	s_add_u32 s18, s33, s0
	s_addc_u32 s19, s34, s1
	s_and_b64 s[0:1], vcc, exec
	s_cselect_b32 s17, s19, s27
	s_cselect_b32 s53, s18, s26
	s_ashr_i32 s15, s14, 31
	s_lshl_b64 s[0:1], s[14:15], 21
	s_add_u32 s20, s4, s0
	s_addc_u32 s21, s5, s1
	s_and_b64 s[0:1], vcc, exec
	s_cselect_b32 s15, s21, s25
	s_cselect_b32 s54, s20, s24
	s_add_u32 s55, s24, 0x100
	s_addc_u32 s56, s25, 0
	s_add_u32 s24, s26, 0x100080
	s_addc_u32 s25, s27, 0
	s_mov_b32 s57, -2
	ds_read_b128 v[152:155], v149
	ds_read_b128 v[156:159], v149 offset:1024
	ds_read_b128 v[160:163], v149 offset:2048
	ds_read_b128 v[164:167], v149 offset:3072
	ds_read_b128 v[168:171], v150
	ds_read_b128 v[172:175], v150 offset:1024
	ds_read_b128 v[176:179], v150 offset:2048
	ds_read_b128 v[180:183], v150 offset:3072
	s_add_u32 s26, s24, 0xfff00080
	s_addc_u32 s27, s25, -1
	s_cmp_eq_u32 s57, 60
	s_cselect_b32 s29, s17, s27
	s_cselect_b32 s28, s53, s26
	s_cselect_b32 s27, s15, s56
	s_cselect_b32 s26, s54, s55
	v_lshl_add_u64 v[146:147], s[24:25], 0, v[140:141]
	s_add_i32 m0, s35, 0xc000
	ds_read_b128 v[184:187], v151
	ds_read_b128 v[188:191], v151 offset:1024
	ds_read_b128 v[192:195], v151 offset:2048
	ds_read_b128 v[196:199], v151 offset:3072
	ds_read_b128 v[200:203], v151 offset:4096
	ds_read_b128 v[204:207], v151 offset:5120
	ds_read_b128 v[208:211], v151 offset:6144
	ds_read_b128 v[212:215], v151 offset:7168
	global_load_lds_dwordx4 v[146:147], off
	v_lshl_add_u64 v[146:147], s[24:25], 0, v[138:139]
	s_add_i32 m0, s35, 0xe000
	s_nop 0
	global_load_lds_dwordx4 v[146:147], off
	s_waitcnt vmcnt(8)
	s_waitcnt lgkmcnt(0)
	s_barrier
	s_waitcnt lgkmcnt(0)
	v_mfma_f32_16x16x32_bf16 v[124:127], v[152:155], v[184:187], 0
	v_mfma_f32_16x16x32_bf16 v[120:123], v[160:163], v[184:187], 0
	v_mfma_f32_16x16x32_bf16 v[116:119], v[152:155], v[192:195], 0
	v_mfma_f32_16x16x32_bf16 v[108:111], v[160:163], v[192:195], 0
	v_mfma_f32_16x16x32_bf16 v[100:103], v[152:155], v[200:203], 0
	v_mfma_f32_16x16x32_bf16 v[92:95], v[160:163], v[200:203], 0
	v_mfma_f32_16x16x32_bf16 v[84:87], v[152:155], v[208:211], 0
	v_mfma_f32_16x16x32_bf16 v[76:79], v[160:163], v[208:211], 0
	v_mfma_f32_16x16x32_bf16 v[124:127], v[156:159], v[188:191], v[124:127]
	v_mfma_f32_16x16x32_bf16 v[120:123], v[164:167], v[188:191], v[120:123]
	v_mfma_f32_16x16x32_bf16 v[116:119], v[156:159], v[196:199], v[116:119]
	v_mfma_f32_16x16x32_bf16 v[108:111], v[164:167], v[196:199], v[108:111]
	v_mfma_f32_16x16x32_bf16 v[100:103], v[156:159], v[204:207], v[100:103]
	v_mfma_f32_16x16x32_bf16 v[92:95], v[164:167], v[204:207], v[92:95]
	v_mfma_f32_16x16x32_bf16 v[84:87], v[156:159], v[212:215], v[84:87]
	v_mfma_f32_16x16x32_bf16 v[76:79], v[164:167], v[212:215], v[76:79]
	v_mfma_f32_16x16x32_bf16 v[112:115], v[168:171], v[184:187], 0
	v_mfma_f32_16x16x32_bf16 v[104:107], v[176:179], v[184:187], 0
	v_mfma_f32_16x16x32_bf16 v[96:99], v[168:171], v[192:195], 0
	v_mfma_f32_16x16x32_bf16 v[88:91], v[176:179], v[192:195], 0
	v_mfma_f32_16x16x32_bf16 v[80:83], v[168:171], v[200:203], 0
	v_mfma_f32_16x16x32_bf16 v[72:75], v[176:179], v[200:203], 0
	v_mfma_f32_16x16x32_bf16 v[68:71], v[168:171], v[208:211], 0
	v_mfma_f32_16x16x32_bf16 v[64:67], v[176:179], v[208:211], 0
	v_mfma_f32_16x16x32_bf16 v[112:115], v[172:175], v[188:191], v[112:115]
	v_mfma_f32_16x16x32_bf16 v[104:107], v[180:183], v[188:191], v[104:107]
	v_mfma_f32_16x16x32_bf16 v[96:99], v[172:175], v[196:199], v[96:99]
	v_mfma_f32_16x16x32_bf16 v[88:91], v[180:183], v[196:199], v[88:91]
	v_mfma_f32_16x16x32_bf16 v[80:83], v[172:175], v[204:207], v[80:83]
	v_mfma_f32_16x16x32_bf16 v[72:75], v[180:183], v[204:207], v[72:75]
	v_mfma_f32_16x16x32_bf16 v[68:71], v[172:175], v[212:215], v[68:71]
	v_mfma_f32_16x16x32_bf16 v[64:67], v[180:183], v[212:215], v[64:67]
	s_barrier
	s_add_i32 s58, s46, s31
	v_lshl_add_u64 v[146:147], s[26:27], 0, v[130:131]
	s_mov_b32 m0, s58
	ds_read_b128 v[184:187], v151 offset:16384
	ds_read_b128 v[188:191], v151 offset:17408
	ds_read_b128 v[192:195], v151 offset:18432
	ds_read_b128 v[196:199], v151 offset:19456
	ds_read_b128 v[200:203], v151 offset:20480
	ds_read_b128 v[204:207], v151 offset:21504
	ds_read_b128 v[208:211], v151 offset:22528
	ds_read_b128 v[212:215], v151 offset:23552
	global_load_lds_dwordx4 v[146:147], off
	s_add_i32 m0, s58, 0x2000
	s_add_u32 s58, s26, 0x100000
	v_lshl_add_u64 v[216:217], s[26:27], 0, v[134:135]
	s_addc_u32 s59, s27, 0
	s_add_i32 s60, s47, s31
	global_load_lds_dwordx4 v[216:217], off
	v_lshl_add_u64 v[218:219], s[58:59], 0, v[130:131]
	s_mov_b32 m0, s60
	v_lshl_add_u64 v[220:221], s[28:29], 0, v[132:133]
	global_load_lds_dwordx4 v[218:219], off
	v_lshl_add_u64 v[218:219], s[58:59], 0, v[134:135]
	s_add_i32 m0, s60, 0x2000
	s_nop 0
	global_load_lds_dwordx4 v[218:219], off
	v_lshl_add_u64 v[218:219], s[28:29], 0, v[128:129]
	s_mov_b32 m0, s35
	s_nop 0
	global_load_lds_dwordx4 v[218:219], off
	s_mov_b32 m0, s36
	s_nop 0
	global_load_lds_dwordx4 v[220:221], off
	s_waitcnt vmcnt(8)
	s_waitcnt lgkmcnt(0)
	s_barrier
	s_waitcnt lgkmcnt(0)
	v_mfma_f32_16x16x32_bf16 v[60:63], v[152:155], v[184:187], 0
	v_mfma_f32_16x16x32_bf16 v[56:59], v[160:163], v[184:187], 0
	v_mfma_f32_16x16x32_bf16 v[52:55], v[152:155], v[192:195], 0
	v_mfma_f32_16x16x32_bf16 v[44:47], v[160:163], v[192:195], 0
	v_mfma_f32_16x16x32_bf16 v[36:39], v[152:155], v[200:203], 0
	v_mfma_f32_16x16x32_bf16 v[28:31], v[160:163], v[200:203], 0
	v_mfma_f32_16x16x32_bf16 v[20:23], v[152:155], v[208:211], 0
	v_mfma_f32_16x16x32_bf16 v[12:15], v[160:163], v[208:211], 0
	v_mfma_f32_16x16x32_bf16 v[60:63], v[156:159], v[188:191], v[60:63]
	v_mfma_f32_16x16x32_bf16 v[56:59], v[164:167], v[188:191], v[56:59]
	v_mfma_f32_16x16x32_bf16 v[52:55], v[156:159], v[196:199], v[52:55]
	v_mfma_f32_16x16x32_bf16 v[44:47], v[164:167], v[196:199], v[44:47]
	v_mfma_f32_16x16x32_bf16 v[36:39], v[156:159], v[204:207], v[36:39]
	v_mfma_f32_16x16x32_bf16 v[28:31], v[164:167], v[204:207], v[28:31]
	v_mfma_f32_16x16x32_bf16 v[20:23], v[156:159], v[212:215], v[20:23]
	v_mfma_f32_16x16x32_bf16 v[12:15], v[164:167], v[212:215], v[12:15]
	v_mfma_f32_16x16x32_bf16 v[48:51], v[168:171], v[184:187], 0
	v_mfma_f32_16x16x32_bf16 v[40:43], v[176:179], v[184:187], 0
	v_mfma_f32_16x16x32_bf16 v[32:35], v[168:171], v[192:195], 0
	v_mfma_f32_16x16x32_bf16 v[24:27], v[176:179], v[192:195], 0
	v_mfma_f32_16x16x32_bf16 v[16:19], v[168:171], v[200:203], 0
	v_mfma_f32_16x16x32_bf16 v[8:11], v[176:179], v[200:203], 0
	v_mfma_f32_16x16x32_bf16 v[4:7], v[168:171], v[208:211], 0
	v_mfma_f32_16x16x32_bf16 v[0:3], v[176:179], v[208:211], 0
	v_mfma_f32_16x16x32_bf16 v[48:51], v[172:175], v[188:191], v[48:51]
	v_mfma_f32_16x16x32_bf16 v[40:43], v[180:183], v[188:191], v[40:43]
	v_mfma_f32_16x16x32_bf16 v[32:35], v[172:175], v[196:199], v[32:35]
	v_mfma_f32_16x16x32_bf16 v[24:27], v[180:183], v[196:199], v[24:27]
	v_mfma_f32_16x16x32_bf16 v[16:19], v[172:175], v[204:207], v[16:19]
	v_mfma_f32_16x16x32_bf16 v[8:11], v[180:183], v[204:207], v[8:11]
	v_mfma_f32_16x16x32_bf16 v[4:7], v[172:175], v[212:215], v[4:7]
	v_mfma_f32_16x16x32_bf16 v[0:3], v[180:183], v[212:215], v[0:3]
	s_barrier
	s_add_i32 s58, 0, 0x18000
	s_add_i32 s59, 0, 0x1c000
	v_add_u32_e32 v164, s58, v148
	v_add_u32_e32 v180, s59, v148
	ds_read_b128 v[152:155], v164
	ds_read_b128 v[156:159], v164 offset:1024
	ds_read_b128 v[160:163], v164 offset:2048
	ds_read_b128 v[164:167], v164 offset:3072
	ds_read_b128 v[168:171], v180
	ds_read_b128 v[172:175], v180 offset:1024
	ds_read_b128 v[176:179], v180 offset:2048
	ds_read_b128 v[180:183], v180 offset:3072
	s_add_u32 s28, s28, 0x100000
	s_addc_u32 s29, s29, 0
	s_mov_b32 m0, s37
	v_lshl_add_u64 v[222:223], s[28:29], 0, v[128:129]
	ds_read_b128 v[184:187], v151 offset:32768
	ds_read_b128 v[188:191], v151 offset:33792
	ds_read_b128 v[192:195], v151 offset:34816
	ds_read_b128 v[196:199], v151 offset:35840
	ds_read_b128 v[200:203], v151 offset:36864
	ds_read_b128 v[204:207], v151 offset:37888
	ds_read_b128 v[208:211], v151 offset:38912
	ds_read_b128 v[212:215], v151 offset:39936
	global_load_lds_dwordx4 v[222:223], off
	v_lshl_add_u64 v[222:223], s[28:29], 0, v[132:133]
	s_mov_b32 m0, s38
	s_nop 0
	global_load_lds_dwordx4 v[222:223], off
	s_waitcnt vmcnt(8)
	s_waitcnt lgkmcnt(0)
	s_barrier
	s_waitcnt lgkmcnt(0)
	v_mfma_f32_16x16x32_bf16 v[124:127], v[152:155], v[184:187], v[124:127]
	v_mfma_f32_16x16x32_bf16 v[120:123], v[160:163], v[184:187], v[120:123]
	v_mfma_f32_16x16x32_bf16 v[116:119], v[152:155], v[192:195], v[116:119]
	v_mfma_f32_16x16x32_bf16 v[108:111], v[160:163], v[192:195], v[108:111]
	v_mfma_f32_16x16x32_bf16 v[100:103], v[152:155], v[200:203], v[100:103]
	v_mfma_f32_16x16x32_bf16 v[92:95], v[160:163], v[200:203], v[92:95]
	v_mfma_f32_16x16x32_bf16 v[84:87], v[152:155], v[208:211], v[84:87]
	v_mfma_f32_16x16x32_bf16 v[76:79], v[160:163], v[208:211], v[76:79]
	v_mfma_f32_16x16x32_bf16 v[124:127], v[156:159], v[188:191], v[124:127]
	v_mfma_f32_16x16x32_bf16 v[120:123], v[164:167], v[188:191], v[120:123]
	v_mfma_f32_16x16x32_bf16 v[116:119], v[156:159], v[196:199], v[116:119]
	v_mfma_f32_16x16x32_bf16 v[108:111], v[164:167], v[196:199], v[108:111]
	v_mfma_f32_16x16x32_bf16 v[100:103], v[156:159], v[204:207], v[100:103]
	v_mfma_f32_16x16x32_bf16 v[92:95], v[164:167], v[204:207], v[92:95]
	v_mfma_f32_16x16x32_bf16 v[84:87], v[156:159], v[212:215], v[84:87]
	v_mfma_f32_16x16x32_bf16 v[76:79], v[164:167], v[212:215], v[76:79]
	v_mfma_f32_16x16x32_bf16 v[112:115], v[168:171], v[184:187], v[112:115]
	v_mfma_f32_16x16x32_bf16 v[104:107], v[176:179], v[184:187], v[104:107]
	v_mfma_f32_16x16x32_bf16 v[96:99], v[168:171], v[192:195], v[96:99]
	v_mfma_f32_16x16x32_bf16 v[88:91], v[176:179], v[192:195], v[88:91]
	v_mfma_f32_16x16x32_bf16 v[80:83], v[168:171], v[200:203], v[80:83]
	v_mfma_f32_16x16x32_bf16 v[72:75], v[176:179], v[200:203], v[72:75]
	v_mfma_f32_16x16x32_bf16 v[68:71], v[168:171], v[208:211], v[68:71]
	v_mfma_f32_16x16x32_bf16 v[64:67], v[176:179], v[208:211], v[64:67]
	v_mfma_f32_16x16x32_bf16 v[112:115], v[172:175], v[188:191], v[112:115]
	v_mfma_f32_16x16x32_bf16 v[104:107], v[180:183], v[188:191], v[104:107]
	v_mfma_f32_16x16x32_bf16 v[96:99], v[172:175], v[196:199], v[96:99]
	v_mfma_f32_16x16x32_bf16 v[88:91], v[180:183], v[196:199], v[88:91]
	v_mfma_f32_16x16x32_bf16 v[80:83], v[172:175], v[204:207], v[80:83]
	v_mfma_f32_16x16x32_bf16 v[72:75], v[180:183], v[204:207], v[72:75]
	v_mfma_f32_16x16x32_bf16 v[68:71], v[172:175], v[212:215], v[68:71]
	v_mfma_f32_16x16x32_bf16 v[64:67], v[180:183], v[212:215], v[64:67]
	s_barrier
	s_add_i32 s28, s58, s31
	v_lshl_add_u64 v[146:147], v[146:147], 0, s[10:11]
	s_mov_b32 m0, s28
	ds_read_b128 v[184:187], v151 offset:49152
	ds_read_b128 v[188:191], v151 offset:50176
	ds_read_b128 v[192:195], v151 offset:51200
	ds_read_b128 v[196:199], v151 offset:52224
	ds_read_b128 v[200:203], v151 offset:53248
	ds_read_b128 v[204:207], v151 offset:54272
	ds_read_b128 v[208:211], v151 offset:55296
	ds_read_b128 v[212:215], v151 offset:56320
	global_load_lds_dwordx4 v[146:147], off
	s_add_i32 m0, s28, 0x2000
	s_add_u32 s26, s26, 0x100080
	v_lshl_add_u64 v[146:147], v[216:217], 0, s[10:11]
	s_addc_u32 s27, s27, 0
	s_add_i32 s28, s59, s31
	global_load_lds_dwordx4 v[146:147], off
	v_lshl_add_u64 v[146:147], s[26:27], 0, v[130:131]
	s_mov_b32 m0, s28
	s_nop 0
	global_load_lds_dwordx4 v[146:147], off
	v_lshl_add_u64 v[146:147], s[26:27], 0, v[134:135]
	s_add_i32 m0, s28, 0x2000
	s_nop 0
	global_load_lds_dwordx4 v[146:147], off
	v_lshl_add_u64 v[146:147], v[218:219], 0, s[10:11]
	s_mov_b32 m0, s41
	s_nop 0
	global_load_lds_dwordx4 v[146:147], off
	v_lshl_add_u64 v[146:147], v[220:221], 0, s[10:11]
	s_mov_b32 m0, s42
	s_nop 0
	global_load_lds_dwordx4 v[146:147], off
	s_waitcnt vmcnt(8)
	s_waitcnt lgkmcnt(0)
	s_barrier
	s_waitcnt lgkmcnt(0)
	v_mfma_f32_16x16x32_bf16 v[60:63], v[152:155], v[184:187], v[60:63]
	v_mfma_f32_16x16x32_bf16 v[56:59], v[160:163], v[184:187], v[56:59]
	v_mfma_f32_16x16x32_bf16 v[52:55], v[152:155], v[192:195], v[52:55]
	v_mfma_f32_16x16x32_bf16 v[44:47], v[160:163], v[192:195], v[44:47]
	v_mfma_f32_16x16x32_bf16 v[36:39], v[152:155], v[200:203], v[36:39]
	v_mfma_f32_16x16x32_bf16 v[28:31], v[160:163], v[200:203], v[28:31]
	v_mfma_f32_16x16x32_bf16 v[20:23], v[152:155], v[208:211], v[20:23]
	v_mfma_f32_16x16x32_bf16 v[12:15], v[160:163], v[208:211], v[12:15]
	v_mfma_f32_16x16x32_bf16 v[60:63], v[156:159], v[188:191], v[60:63]
	v_mfma_f32_16x16x32_bf16 v[56:59], v[164:167], v[188:191], v[56:59]
	v_mfma_f32_16x16x32_bf16 v[52:55], v[156:159], v[196:199], v[52:55]
	v_mfma_f32_16x16x32_bf16 v[44:47], v[164:167], v[196:199], v[44:47]
	v_mfma_f32_16x16x32_bf16 v[36:39], v[156:159], v[204:207], v[36:39]
	v_mfma_f32_16x16x32_bf16 v[28:31], v[164:167], v[204:207], v[28:31]
	v_mfma_f32_16x16x32_bf16 v[20:23], v[156:159], v[212:215], v[20:23]
	v_mfma_f32_16x16x32_bf16 v[12:15], v[164:167], v[212:215], v[12:15]
	v_mfma_f32_16x16x32_bf16 v[48:51], v[168:171], v[184:187], v[48:51]
	v_mfma_f32_16x16x32_bf16 v[40:43], v[176:179], v[184:187], v[40:43]
	v_mfma_f32_16x16x32_bf16 v[32:35], v[168:171], v[192:195], v[32:35]
	v_mfma_f32_16x16x32_bf16 v[24:27], v[176:179], v[192:195], v[24:27]
	v_mfma_f32_16x16x32_bf16 v[16:19], v[168:171], v[200:203], v[16:19]
	v_mfma_f32_16x16x32_bf16 v[8:11], v[176:179], v[200:203], v[8:11]
	v_mfma_f32_16x16x32_bf16 v[4:7], v[168:171], v[208:211], v[4:7]
	v_mfma_f32_16x16x32_bf16 v[0:3], v[176:179], v[208:211], v[0:3]
	v_mfma_f32_16x16x32_bf16 v[48:51], v[172:175], v[188:191], v[48:51]
	v_mfma_f32_16x16x32_bf16 v[40:43], v[180:183], v[188:191], v[40:43]
	v_mfma_f32_16x16x32_bf16 v[32:35], v[172:175], v[196:199], v[32:35]
	v_mfma_f32_16x16x32_bf16 v[24:27], v[180:183], v[196:199], v[24:27]
	v_mfma_f32_16x16x32_bf16 v[16:19], v[172:175], v[204:207], v[16:19]
	v_mfma_f32_16x16x32_bf16 v[8:11], v[180:183], v[204:207], v[8:11]
	v_mfma_f32_16x16x32_bf16 v[4:7], v[172:175], v[212:215], v[4:7]
	v_mfma_f32_16x16x32_bf16 v[0:3], v[180:183], v[212:215], v[0:3]
	s_barrier
	s_add_i32 s57, s57, 2
	s_add_u32 s55, s55, 0x100
	s_addc_u32 s56, s56, 0
	s_add_u32 s24, s24, 0x100
	s_addc_u32 s25, s25, 0
	s_cmp_lt_u32 s57, 62
	s_nop 0
